# FFN1 epilogue: second row-batch ssq loads issued with the first batch (free fragment registers), removing waits behind first-batch stores; on top of final combined
# baseline (speedup 1.0000x reference)
; __device__ __forceinline__ float fast_sigmoid(float v) { return __builtin_amdgcn_rcpf(1.0f + __builtin_amdgcn_exp2f(-1.4426950408889634f * v)); }
; __device__ __forceinline__ u32x4 pack8(const float* v) { u32x4 w; w.x = cvt_pk_bf16(v[0], v[1]); w.y = cvt_pk_bf16(v[2], v[3]); w.z = cvt_pk_bf16(v[4], v[5]); w.w = cvt_pk_bf16(v[6], v[7]); return w; }
;     __device__ __forceinline__ void operator()(int row, int pn, int within, const float* a, const float* b, float) const { (void)apply(row, pn, within, a, b); }
;     __device__ __forceinline__ void operator()(int row, int pn, int within, const float* a, const float* b, float) const { Pre p = preload(row, pn, within, 0); finish(row, pn, within, a, b, p); }
; #define PG8_GATHER(ai, m) float a[8], b[8]; _Pragma("unroll") for (int j = 0; j < 4; ++j) { a[j] = acc[ai][0][m][0][j]; a[4 + j] = acc[ai][0][m][1][j]; b[j] = acc[ai][1][m][0][j]; b[4 + j] = acc[ai][1][m][1][j]; }
;     __device__ __forceinline__ void finish(int row, int pn, int within, const float* a, const float* b, const Pre& p) const {
;         const f32x4 s4 = p.s0 + p.s1; float sm = (s4[0] + s4[1]) + (s4[2] + s4[3]); sm += __shfl_xor(sm, 16); sm += __shfl_xor(sm, 32);
;         (*this)(row, pn, within, a, b, __builtin_amdgcn_rsqf(sm * (1.0f / DM) + EPS)); }
;     __device__ __forceinline__ void operator()(int row, int pn, int within, const float* a, const float* b, float rc) const {
;         float o[8];
; #pragma unroll
;         for (int j = 0; j < 8; ++j) { const float g = a[j] * rc, u = b[j] * rc; o[j] = g * fast_sigmoid(g) * u; }
;         *(u32x4*)(hidden + (size_t)row * DFF + pn * 128 + within) = pack8(o);
; template <class Epi> __device__ __forceinline__ void run_epi(const Epi& E, const f32x4 (&acc)[2][2][4][2], const Unit& u, int wr, int wc, int fr, int fq) {
;     ...
;     for (int ai = 0; ai < 2; ++ai) { const int row0 = u.pm * BM + ai * HALF + wr * 64 + fr; typename Epi::Pre pre[4];
; #pragma unroll
;         for (int m = 0; m < 4; ++m) pre[m] = E.preload(row0 + m * 16, u.pn, within, fq);
; #pragma unroll
;         for (int m = 0; m < 4; ++m) { PG8_GATHER(ai, m); E.finish(row0 + m * 16, u.pn, within, a, b, pre[m]); } }
.LBB0_599:
	s_lshl_b32 s17, s24, 8
	v_mov_b32_e32 v128, v165
	v_mov_b32_e32 v129, v164
	s_add_i32 s17, s17, s44
	s_lshl_b32 s24, s25, 7
	v_lshlrev_b32_e32 v158, 3, v128
	v_add_u32_e32 v154, s17, v129
	v_ashrrev_i32_e32 v159, 31, v158
	v_ashrrev_i32_e32 v155, 31, v154
	v_lshl_add_u64 v[156:157], v[158:159], 2, s[8:9]
	v_lshlrev_b64 v[128:129], 7, v[154:155]
	v_lshl_add_u64 v[132:133], v[156:157], 0, v[128:129]
	global_load_dwordx4 v[128:131], v[132:133], off
	s_nop 0
	global_load_dwordx4 v[132:135], v[132:133], off offset:16
	v_add_u32_e32 v160, 16, v154
	v_ashrrev_i32_e32 v161, 31, v160
	v_lshlrev_b64 v[152:153], 7, v[160:161]
	v_lshl_add_u64 v[152:153], v[156:157], 0, v[152:153]
	global_load_dwordx4 v[172:175], v[152:153], off
	global_load_dwordx4 v[176:179], v[152:153], off offset:16
	v_and_b32_e32 v159, 64, v170
	v_xor_b32_e32 v155, 16, v170
	v_add_u32_e32 v159, 64, v159
	v_xor_b32_e32 v161, 32, v170
	v_cmp_lt_i32_e32 vcc, v155, v159
	v_add_u32_e32 v162, 32, v154
	v_add_u32_e32 v188, s45, v158
	v_cndmask_b32_e32 v155, v170, v155, vcc
	v_cmp_lt_i32_e32 vcc, v161, v159
	v_add_u32_e32 v158, 48, v154
	v_ashrrev_i32_e32 v163, 31, v162
	v_cndmask_b32_e32 v159, v170, v161, vcc
	v_lshlrev_b32_e32 v161, 2, v155
	v_lshlrev_b32_e32 v155, 2, v159
	v_ashrrev_i32_e32 v159, 31, v158
	v_lshlrev_b64 v[180:181], 7, v[162:163]
	v_lshlrev_b64 v[182:183], 7, v[158:159]
	v_lshl_add_u64 v[184:185], v[156:157], 0, v[180:181]
	v_lshl_add_u64 v[190:191], v[156:157], 0, v[182:183]
	global_load_dwordx4 v[180:183], v[184:185], off
	s_nop 0
	global_load_dwordx4 v[184:187], v[184:185], off offset:16
	v_mov_b64_e32 v[152:153], s[10:11]
	s_ashr_i32 s25, s24, 31
	v_ashrrev_i32_e32 v189, 31, v188
	s_lshl_b64 s[24:25], s[24:25], 1
	s_andn2_b64 vcc, exec, s[0:1]
	s_mov_b64 s[0:1], -1
	v_add_u32_e32 v192, 128, v154
	v_ashrrev_i32_e32 v193, 31, v192
	v_lshlrev_b64 v[192:193], 7, v[192:193]
	v_lshl_add_u64 v[192:193], v[156:157], 0, v[192:193]
	global_load_dwordx4 v[196:199], v[192:193], off
	global_load_dwordx4 v[200:203], v[192:193], off offset:16
	v_add_u32_e32 v192, 144, v154
	v_ashrrev_i32_e32 v193, 31, v192
	v_lshlrev_b64 v[192:193], 7, v[192:193]
	v_lshl_add_u64 v[192:193], v[156:157], 0, v[192:193]
	global_load_dwordx4 v[204:207], v[192:193], off
	global_load_dwordx4 v[208:211], v[192:193], off offset:16
	v_add_u32_e32 v192, 160, v154
	v_ashrrev_i32_e32 v193, 31, v192
	v_lshlrev_b64 v[192:193], 7, v[192:193]
	v_lshl_add_u64 v[192:193], v[156:157], 0, v[192:193]
	global_load_dwordx4 v[212:215], v[192:193], off
	global_load_dwordx4 v[216:219], v[192:193], off offset:16
	v_add_u32_e32 v192, 176, v154
	v_ashrrev_i32_e32 v193, 31, v192
	v_lshlrev_b64 v[192:193], 7, v[192:193]
	v_lshl_add_u64 v[192:193], v[156:157], 0, v[192:193]
	global_load_dwordx4 v[220:223], v[192:193], off
	global_load_dwordx4 v[224:227], v[192:193], off offset:16
	s_waitcnt vmcnt(0)
	v_pk_add_f32 v[130:131], v[130:131], v[134:135]
	v_pk_add_f32 v[128:129], v[128:129], v[132:133]
	s_nop 0
	v_pk_mov_b32 v[132:133], v[128:129], v[130:131] op_sel:[1,0]
	v_mov_b32_e32 v129, v131
	v_pk_add_f32 v[128:129], v[132:133], v[128:129]
	v_pk_add_f32 v[130:131], v[172:173], v[176:177]
	v_add_f32_e32 v134, v128, v129
	ds_bpermute_b32 v135, v161, v134
	v_pk_add_f32 v[128:129], v[174:175], v[178:179]
	s_waitcnt lgkmcnt(0)
	v_add_f32_e32 v134, v134, v135
	ds_bpermute_b32 v135, v155, v134
	v_pk_mov_b32 v[132:133], v[130:131], v[128:129] op_sel:[1,0]
	v_mov_b32_e32 v131, v129
	v_pk_add_f32 v[128:129], v[132:133], v[130:131]
	s_nop 0
	v_add_f32_e32 v159, v128, v129
	s_waitcnt lgkmcnt(0)
	v_add_f32_e32 v128, v134, v135
	v_fmamk_f32 v128, v128, 0x3a000000, v171
	v_rsq_f32_e32 v172, v128
	ds_bpermute_b32 v163, v161, v159
	global_load_dwordx4 v[128:131], v[190:191], off
	global_load_dwordx4 v[132:135], v[190:191], off offset:16
	v_pk_mul_f32 v[126:127], v[126:127], v[172:173] op_sel_hi:[1,0]
	v_pk_mul_f32 v[120:121], v[120:121], v[172:173] op_sel_hi:[1,0]
	v_pk_mul_f32 v[122:123], v[122:123], v[172:173] op_sel_hi:[1,0]
	v_mul_f32_e32 v174, 0xbfb8aa3b, v126
	v_mul_f32_e32 v175, 0xbfb8aa3b, v127
	v_mul_f32_e32 v176, 0xbfb8aa3b, v120
	v_mul_f32_e32 v177, 0xbfb8aa3b, v121
	v_mul_f32_e32 v178, 0xbfb8aa3b, v122
	v_mul_f32_e32 v179, 0xbfb8aa3b, v123
	v_exp_f32_e32 v174, v174
	v_exp_f32_e32 v175, v175
	v_exp_f32_e32 v176, v176
	v_exp_f32_e32 v177, v177
	v_exp_f32_e32 v178, v178
	v_exp_f32_e32 v179, v179
	v_add_f32_e32 v174, 1.0, v174
	v_add_f32_e32 v175, 1.0, v175
	s_waitcnt lgkmcnt(0)
	v_add_f32_e32 v159, v159, v163
	v_add_f32_e32 v176, 1.0, v176
	v_add_f32_e32 v177, 1.0, v177
	v_add_f32_e32 v178, 1.0, v178
	v_add_f32_e32 v179, 1.0, v179
	v_rcp_f32_e32 v174, v174
	v_rcp_f32_e32 v175, v175
	ds_bpermute_b32 v163, v155, v159
	v_rcp_f32_e32 v176, v176
	v_rcp_f32_e32 v177, v177
	v_rcp_f32_e32 v178, v178
	v_rcp_f32_e32 v179, v179
	v_pk_mul_f32 v[124:125], v[124:125], v[172:173] op_sel_hi:[1,0]
	v_pk_mul_f32 v[116:117], v[116:117], v[172:173] op_sel_hi:[1,0]
	v_pk_mul_f32 v[118:119], v[118:119], v[172:173] op_sel_hi:[1,0]
	v_pk_mul_f32 v[112:113], v[112:113], v[172:173] op_sel_hi:[1,0]
	v_pk_mul_f32 v[114:115], v[114:115], v[172:173] op_sel_hi:[1,0]
	v_mul_f32_e32 v172, 0xbfb8aa3b, v124
	v_mul_f32_e32 v173, 0xbfb8aa3b, v125
	v_exp_f32_e32 v172, v172
	v_exp_f32_e32 v173, v173
	v_pk_mul_f32 v[126:127], v[126:127], v[174:175]
	v_pk_mul_f32 v[120:121], v[120:121], v[176:177]
	v_pk_mul_f32 v[122:123], v[122:123], v[178:179]
	v_pk_mul_f32 v[118:119], v[118:119], v[126:127]
	v_pk_mul_f32 v[112:113], v[112:113], v[120:121]
	v_pk_mul_f32 v[120:121], v[114:115], v[122:123]
	v_cvt_pk_bf16_f32 v115, v118, v119
	s_waitcnt lgkmcnt(0)
; __device__ __forceinline__ float fast_sigmoid(float v) { return __builtin_amdgcn_rcpf(1.0f + __builtin_amdgcn_exp2f(-1.4426950408889634f * v)); }
; __device__ __forceinline__ u32x4 pack8(const float* v) { u32x4 w; w.x = cvt_pk_bf16(v[0], v[1]); w.y = cvt_pk_bf16(v[2], v[3]); w.z = cvt_pk_bf16(v[4], v[5]); w.w = cvt_pk_bf16(v[6], v[7]); return w; }
;     __device__ __forceinline__ void operator()(int row, int pn, int within, const float* a, const float* b, float) const { (void)apply(row, pn, within, a, b); }
;     __device__ __forceinline__ void operator()(int row, int pn, int within, const float* a, const float* b, float) const { Pre p = preload(row, pn, within, 0); finish(row, pn, within, a, b, p); }
;     __device__ __forceinline__ void finish(int row, int pn, int within, const float* a, const float* b, const Pre& p) const {
;         const f32x4 s4 = p.s0 + p.s1; float sm = (s4[0] + s4[1]) + (s4[2] + s4[3]); sm += __shfl_xor(sm, 16); sm += __shfl_xor(sm, 32);
;         (*this)(row, pn, within, a, b, __builtin_amdgcn_rsqf(sm * (1.0f / DM) + EPS)); }
;     __device__ __forceinline__ void operator()(int row, int pn, int within, const float* a, const float* b, float rc) const {
;         float o[8];
; #pragma unroll
;         for (int j = 0; j < 8; ++j) { const float g = a[j] * rc, u = b[j] * rc; o[j] = g * fast_sigmoid(g) * u; }
;         *(u32x4*)(hidden + (size_t)row * DFF + pn * 128 + within) = pack8(o);
	v_add_f32_e32 v118, v159, v163
	v_fmamk_f32 v118, v118, 0x3a000000, v171
	v_add_f32_e32 v172, 1.0, v172
	v_add_f32_e32 v173, 1.0, v173
	v_rsq_f32_e32 v118, v118
	v_rcp_f32_e32 v172, v172
	v_rcp_f32_e32 v173, v173
	v_pk_mul_f32 v[108:109], v[108:109], v[118:119] op_sel_hi:[1,0]
	s_nop 0
	v_mul_f32_e32 v119, 0xbfb8aa3b, v108
	v_pk_mul_f32 v[124:125], v[124:125], v[172:173]
	v_exp_f32_e32 v119, v119
	v_pk_mul_f32 v[116:117], v[116:117], v[124:125]
	v_pk_mul_f32 v[110:111], v[110:111], v[118:119] op_sel_hi:[1,0]
	v_cvt_pk_bf16_f32 v114, v116, v117
	v_cvt_pk_bf16_f32 v116, v112, v113
	v_mad_i64_i32 v[112:113], s[26:27], v154, s52, v[152:153]
	v_cvt_pk_bf16_f32 v117, v120, v121
	v_lshl_add_u64 v[120:121], v[112:113], 0, s[24:25]
	v_lshlrev_b64 v[112:113], 1, v[188:189]
	v_lshl_add_u64 v[120:121], v[120:121], 0, v[112:113]
	global_store_dwordx4 v[120:121], v[114:117], off
	v_pk_mul_f32 v[100:101], v[100:101], v[118:119] op_sel_hi:[1,0]
	v_pk_mul_f32 v[102:103], v[102:103], v[118:119] op_sel_hi:[1,0]
	v_mul_f32_e32 v114, 0xbfb8aa3b, v109
	v_exp_f32_e32 v115, v114
	v_mul_f32_e32 v116, 0xbfb8aa3b, v110
	v_mul_f32_e32 v117, 0xbfb8aa3b, v111
	v_exp_f32_e32 v116, v116
	v_exp_f32_e32 v117, v117
	v_add_f32_e32 v114, 1.0, v119
	v_add_f32_e32 v115, 1.0, v115
	v_rcp_f32_e32 v114, v114
	v_rcp_f32_e32 v115, v115
	v_add_f32_e32 v116, 1.0, v116
	v_add_f32_e32 v117, 1.0, v117
	v_rcp_f32_e32 v116, v116
	v_rcp_f32_e32 v117, v117
	v_pk_mul_f32 v[108:109], v[108:109], v[114:115]
	v_pk_mul_f32 v[104:105], v[104:105], v[118:119] op_sel_hi:[1,0]
	v_pk_mul_f32 v[100:101], v[100:101], v[108:109]
	v_pk_mul_f32 v[108:109], v[110:111], v[116:117]
	v_mul_f32_e32 v110, 0xbfb8aa3b, v104
	v_pk_mul_f32 v[102:103], v[102:103], v[108:109]
	v_mul_f32_e32 v108, 0xbfb8aa3b, v105
	v_exp_f32_e32 v110, v110
	v_exp_f32_e32 v109, v108
	v_pk_mul_f32 v[106:107], v[106:107], v[118:119] op_sel_hi:[1,0]
	v_pk_add_f32 v[114:115], v[180:181], v[184:185]
	v_add_f32_e32 v108, 1.0, v110
	v_add_f32_e32 v109, 1.0, v109
	v_mul_f32_e32 v110, 0xbfb8aa3b, v106
	v_mul_f32_e32 v111, 0xbfb8aa3b, v107
	v_rcp_f32_e32 v108, v108
	v_rcp_f32_e32 v109, v109
	v_exp_f32_e32 v110, v110
	v_exp_f32_e32 v111, v111
	v_pk_mul_f32 v[96:97], v[96:97], v[118:119] op_sel_hi:[1,0]
	v_pk_mul_f32 v[104:105], v[104:105], v[108:109]
	v_add_f32_e32 v108, 1.0, v110
	v_add_f32_e32 v109, 1.0, v111
	v_pk_add_f32 v[110:111], v[182:183], v[186:187]
	v_rcp_f32_e32 v108, v108
	v_pk_mov_b32 v[116:117], v[114:115], v[110:111] op_sel:[1,0]
	v_mov_b32_e32 v115, v111
	v_pk_add_f32 v[110:111], v[116:117], v[114:115]
	v_rcp_f32_e32 v109, v109
	v_add_f32_e32 v110, v110, v111
	ds_bpermute_b32 v111, v161, v110
	v_pk_mul_f32 v[104:105], v[96:97], v[104:105]
	v_pk_mul_f32 v[96:97], v[98:99], v[118:119] op_sel_hi:[1,0]
	v_pk_mul_f32 v[98:99], v[106:107], v[108:109]
	s_waitcnt lgkmcnt(0)
	v_add_f32_e32 v108, v110, v111
	ds_bpermute_b32 v109, v155, v108
	v_pk_mul_f32 v[106:107], v[96:97], v[98:99]
	v_cvt_pk_bf16_f32 v96, v100, v101
	v_cvt_pk_bf16_f32 v97, v102, v103
	v_mad_i64_i32 v[102:103], s[26:27], v160, s52, v[152:153]
	s_waitcnt lgkmcnt(0)
	v_add_f32_e32 v100, v108, v109
	v_fmamk_f32 v100, v100, 0x3a000000, v171
	v_rsq_f32_e32 v100, v100
	v_lshl_add_u64 v[102:103], v[102:103], 0, s[24:25]
	v_cvt_pk_bf16_f32 v98, v104, v105
	v_cvt_pk_bf16_f32 v99, v106, v107
	v_pk_mul_f32 v[92:93], v[92:93], v[100:101] op_sel_hi:[1,0]
	v_lshl_add_u64 v[102:103], v[102:103], 0, v[112:113]
	v_mul_f32_e32 v101, 0xbfb8aa3b, v92
	v_exp_f32_e32 v101, v101
	global_store_dwordx4 v[102:103], v[96:99], off
	v_pk_mul_f32 v[94:95], v[94:95], v[100:101] op_sel_hi:[1,0]
	s_nop 0
	v_mul_f32_e32 v96, 0xbfb8aa3b, v93
	v_exp_f32_e32 v97, v96
	v_mul_f32_e32 v98, 0xbfb8aa3b, v94
	v_mul_f32_e32 v99, 0xbfb8aa3b, v95
	v_exp_f32_e32 v98, v98
	v_exp_f32_e32 v99, v99
	v_add_f32_e32 v96, 1.0, v101
	v_add_f32_e32 v97, 1.0, v97
	v_rcp_f32_e32 v96, v96
	v_rcp_f32_e32 v97, v97
	v_add_f32_e32 v98, 1.0, v98
	v_add_f32_e32 v99, 1.0, v99
	v_rcp_f32_e32 v98, v98
	v_rcp_f32_e32 v99, v99
	v_pk_mul_f32 v[84:85], v[84:85], v[100:101] op_sel_hi:[1,0]
	v_pk_mul_f32 v[92:93], v[92:93], v[96:97]
	v_pk_mul_f32 v[86:87], v[86:87], v[100:101] op_sel_hi:[1,0]
	v_pk_mul_f32 v[84:85], v[84:85], v[92:93]
	v_pk_mul_f32 v[92:93], v[94:95], v[98:99]
	v_pk_mul_f32 v[88:89], v[88:89], v[100:101] op_sel_hi:[1,0]
	v_pk_mul_f32 v[86:87], v[86:87], v[92:93]
	v_mul_f32_e32 v94, 0xbfb8aa3b, v88
	v_mul_f32_e32 v92, 0xbfb8aa3b, v89
	v_exp_f32_e32 v94, v94
	v_exp_f32_e32 v93, v92
	v_pk_mul_f32 v[90:91], v[90:91], v[100:101] op_sel_hi:[1,0]
	s_waitcnt vmcnt(2)
	v_pk_add_f32 v[96:97], v[128:129], v[132:133]
	v_add_f32_e32 v92, 1.0, v94
	v_add_f32_e32 v93, 1.0, v93
	v_mul_f32_e32 v94, 0xbfb8aa3b, v90
	v_mul_f32_e32 v95, 0xbfb8aa3b, v91
	v_rcp_f32_e32 v92, v92
	v_rcp_f32_e32 v93, v93
	v_exp_f32_e32 v94, v94
	v_exp_f32_e32 v95, v95
	v_pk_mul_f32 v[80:81], v[80:81], v[100:101] op_sel_hi:[1,0]
	v_pk_mul_f32 v[88:89], v[88:89], v[92:93]
	v_add_f32_e32 v92, 1.0, v94
	v_add_f32_e32 v93, 1.0, v95
	v_pk_add_f32 v[94:95], v[130:131], v[134:135]
	v_rcp_f32_e32 v92, v92
	v_pk_mov_b32 v[98:99], v[96:97], v[94:95] op_sel:[1,0]
	v_mov_b32_e32 v97, v95
	v_pk_add_f32 v[94:95], v[98:99], v[96:97]
	v_rcp_f32_e32 v93, v93
	v_add_f32_e32 v94, v94, v95
	ds_bpermute_b32 v95, v161, v94
	v_pk_mul_f32 v[88:89], v[80:81], v[88:89]
	v_pk_mul_f32 v[80:81], v[82:83], v[100:101] op_sel_hi:[1,0]
	v_pk_mul_f32 v[82:83], v[90:91], v[92:93]
	s_waitcnt lgkmcnt(0)
	v_add_f32_e32 v92, v94, v95
	ds_bpermute_b32 v93, v155, v92
	v_pk_mul_f32 v[90:91], v[80:81], v[82:83]
	v_cvt_pk_bf16_f32 v80, v84, v85
	v_cvt_pk_bf16_f32 v81, v86, v87
	v_mad_i64_i32 v[86:87], s[26:27], v162, s52, v[152:153]
	s_waitcnt lgkmcnt(0)
; __device__ __forceinline__ float fast_sigmoid(float v) { return __builtin_amdgcn_rcpf(1.0f + __builtin_amdgcn_exp2f(-1.4426950408889634f * v)); }
; __device__ __forceinline__ u32x4 pack8(const float* v) { u32x4 w; w.x = cvt_pk_bf16(v[0], v[1]); w.y = cvt_pk_bf16(v[2], v[3]); w.z = cvt_pk_bf16(v[4], v[5]); w.w = cvt_pk_bf16(v[6], v[7]); return w; }
;     __device__ __forceinline__ void operator()(int row, int pn, int within, const float* a, const float* b, float) const { (void)apply(row, pn, within, a, b); }
;     __device__ __forceinline__ void operator()(int row, int pn, int within, const float* a, const float* b, float) const { Pre p = preload(row, pn, within, 0); finish(row, pn, within, a, b, p); }
; #define PG8_GATHER(ai, m) float a[8], b[8]; _Pragma("unroll") for (int j = 0; j < 4; ++j) { a[j] = acc[ai][0][m][0][j]; a[4 + j] = acc[ai][0][m][1][j]; b[j] = acc[ai][1][m][0][j]; b[4 + j] = acc[ai][1][m][1][j]; }
;     __device__ __forceinline__ void finish(int row, int pn, int within, const float* a, const float* b, const Pre& p) const {
;         const f32x4 s4 = p.s0 + p.s1; float sm = (s4[0] + s4[1]) + (s4[2] + s4[3]); sm += __shfl_xor(sm, 16); sm += __shfl_xor(sm, 32);
;         (*this)(row, pn, within, a, b, __builtin_amdgcn_rsqf(sm * (1.0f / DM) + EPS)); }
;     __device__ __forceinline__ void operator()(int row, int pn, int within, const float* a, const float* b, float rc) const {
;         float o[8];
; #pragma unroll
;         for (int j = 0; j < 8; ++j) { const float g = a[j] * rc, u = b[j] * rc; o[j] = g * fast_sigmoid(g) * u; }
;         *(u32x4*)(hidden + (size_t)row * DFF + pn * 128 + within) = pack8(o);
; template <class Epi> __device__ __forceinline__ void run_epi(const Epi& E, const f32x4 (&acc)[2][2][4][2], const Unit& u, int wr, int wc, int fr, int fq) {
;     ...
;     for (int ai = 0; ai < 2; ++ai) { const int row0 = u.pm * BM + ai * HALF + wr * 64 + fr; typename Epi::Pre pre[4];
; #pragma unroll
;         for (int m = 0; m < 4; ++m) pre[m] = E.preload(row0 + m * 16, u.pn, within, fq);
; #pragma unroll
;         for (int m = 0; m < 4; ++m) { PG8_GATHER(ai, m); E.finish(row0 + m * 16, u.pn, within, a, b, pre[m]); } }
	v_add_f32_e32 v84, v92, v93
	v_fmamk_f32 v84, v84, 0x3a000000, v171
	v_rsq_f32_e32 v84, v84
	v_lshl_add_u64 v[86:87], v[86:87], 0, s[24:25]
	v_cvt_pk_bf16_f32 v82, v88, v89
	v_cvt_pk_bf16_f32 v83, v90, v91
	v_pk_mul_f32 v[76:77], v[76:77], v[84:85] op_sel_hi:[1,0]
	v_lshl_add_u64 v[86:87], v[86:87], 0, v[112:113]
	v_mul_f32_e32 v85, 0xbfb8aa3b, v76
	v_exp_f32_e32 v85, v85
	global_store_dwordx4 v[86:87], v[80:83], off
	v_add_u32_e32 v94, 0x80, v154
	v_ashrrev_i32_e32 v95, 31, v94
	v_mul_f32_e32 v80, 0xbfb8aa3b, v77
	v_pk_mul_f32 v[78:79], v[78:79], v[84:85] op_sel_hi:[1,0]
	v_exp_f32_e32 v81, v80
	v_mul_f32_e32 v82, 0xbfb8aa3b, v78
	v_mul_f32_e32 v83, 0xbfb8aa3b, v79
	v_exp_f32_e32 v82, v82
	v_exp_f32_e32 v83, v83
	v_add_f32_e32 v80, 1.0, v85
	v_add_f32_e32 v81, 1.0, v81
	v_rcp_f32_e32 v80, v80
	v_rcp_f32_e32 v81, v81
	v_add_f32_e32 v82, 1.0, v82
	v_add_f32_e32 v83, 1.0, v83
	v_rcp_f32_e32 v82, v82
	v_rcp_f32_e32 v83, v83
	v_pk_mul_f32 v[68:69], v[68:69], v[84:85] op_sel_hi:[1,0]
	v_pk_mul_f32 v[76:77], v[76:77], v[80:81]
	v_pk_mul_f32 v[72:73], v[72:73], v[84:85] op_sel_hi:[1,0]
	v_pk_mul_f32 v[68:69], v[68:69], v[76:77]
	v_pk_mul_f32 v[76:77], v[78:79], v[82:83]
	v_mul_f32_e32 v78, 0xbfb8aa3b, v72
	v_exp_f32_e32 v78, v78
	v_pk_mul_f32 v[70:71], v[70:71], v[84:85] op_sel_hi:[1,0]
	v_pk_mul_f32 v[74:75], v[74:75], v[84:85] op_sel_hi:[1,0]
	v_pk_mul_f32 v[70:71], v[70:71], v[76:77]
	v_mul_f32_e32 v76, 0xbfb8aa3b, v73
	v_exp_f32_e32 v77, v76
	v_add_f32_e32 v76, 1.0, v78
	v_mul_f32_e32 v78, 0xbfb8aa3b, v74
	v_mul_f32_e32 v79, 0xbfb8aa3b, v75
	v_exp_f32_e32 v78, v78
	v_exp_f32_e32 v79, v79
	v_add_f32_e32 v77, 1.0, v77
	v_rcp_f32_e32 v76, v76
	v_rcp_f32_e32 v77, v77
	v_add_f32_e32 v78, 1.0, v78
	v_add_f32_e32 v79, 1.0, v79
	v_rcp_f32_e32 v78, v78
	v_rcp_f32_e32 v79, v79
	v_pk_mul_f32 v[64:65], v[64:65], v[84:85] op_sel_hi:[1,0]
	v_pk_mul_f32 v[72:73], v[72:73], v[76:77]
	v_add_u32_e32 v76, 0x90, v154
	v_pk_mul_f32 v[72:73], v[64:65], v[72:73]
	v_pk_mul_f32 v[64:65], v[66:67], v[84:85] op_sel_hi:[1,0]
	v_pk_mul_f32 v[66:67], v[74:75], v[78:79]
	v_ashrrev_i32_e32 v77, 31, v76
	v_pk_mul_f32 v[74:75], v[64:65], v[66:67]
	v_cvt_pk_bf16_f32 v64, v68, v69
	v_mad_i64_i32 v[68:69], s[26:27], v158, s52, v[152:153]
	v_lshl_add_u64 v[68:69], v[68:69], 0, s[24:25]
	v_cvt_pk_bf16_f32 v65, v70, v71
	v_cvt_pk_bf16_f32 v66, v72, v73
	v_cvt_pk_bf16_f32 v67, v74, v75
	v_lshl_add_u64 v[68:69], v[68:69], 0, v[112:113]
	global_store_dwordx4 v[68:69], v[64:67], off
	v_lshlrev_b64 v[72:73], 7, v[76:77]
	v_lshl_add_u64 v[72:73], v[156:157], 0, v[72:73]
	v_lshlrev_b64 v[64:65], 7, v[94:95]
	v_lshl_add_u64 v[68:69], v[156:157], 0, v[64:65]
	v_mov_b64_e32 v[64:65], v[196:197]
	v_mov_b64_e32 v[66:67], v[198:199]
	s_nop 0
	v_mov_b64_e32 v[68:69], v[200:201]
	v_mov_b64_e32 v[70:71], v[202:203]
	s_nop 0
	v_mov_b64_e32 v[78:79], v[204:205]
	v_mov_b64_e32 v[80:81], v[206:207]
	v_mov_b64_e32 v[82:83], v[208:209]
	v_mov_b64_e32 v[84:85], v[210:211]
	v_add_u32_e32 v74, 0xa0, v154
	v_ashrrev_i32_e32 v75, 31, v74
	v_add_u32_e32 v72, 0xb0, v154
	v_ashrrev_i32_e32 v73, 31, v72
	v_pk_add_f32 v[66:67], v[66:67], v[70:71]
	v_pk_add_f32 v[64:65], v[64:65], v[68:69]
	v_pk_add_f32 v[78:79], v[78:79], v[82:83]
	v_pk_mov_b32 v[68:69], v[64:65], v[66:67] op_sel:[1,0]
	v_mov_b32_e32 v65, v67
	v_pk_add_f32 v[64:65], v[68:69], v[64:65]
	s_nop 0
	v_add_f32_e32 v66, v64, v65
	ds_bpermute_b32 v67, v161, v66
	v_lshlrev_b64 v[64:65], 7, v[74:75]
	v_lshl_add_u64 v[64:65], v[156:157], 0, v[64:65]
	v_mov_b64_e32 v[86:87], v[212:213]
	v_mov_b64_e32 v[88:89], v[214:215]
	v_mov_b64_e32 v[90:91], v[216:217]
	v_mov_b64_e32 v[92:93], v[218:219]
	s_waitcnt lgkmcnt(0)
	v_add_f32_e32 v66, v66, v67
	ds_bpermute_b32 v67, v155, v66
	s_waitcnt lgkmcnt(0)
	v_add_f32_e32 v64, v66, v67
	v_fmamk_f32 v64, v64, 0x3a000000, v171
	v_rsq_f32_e32 v96, v64
	v_lshlrev_b64 v[64:65], 7, v[72:73]
	v_lshl_add_u64 v[68:69], v[156:157], 0, v[64:65]
	v_pk_mul_f32 v[60:61], v[60:61], v[96:97] op_sel_hi:[1,0]
	s_nop 0
	v_mul_f32_e32 v64, 0xbfb8aa3b, v60
	v_exp_f32_e32 v73, v64
	v_mul_f32_e32 v75, 0xbfb8aa3b, v61
	v_exp_f32_e32 v75, v75
	v_pk_mul_f32 v[62:63], v[62:63], v[96:97] op_sel_hi:[1,0]
	v_add_f32_e32 v73, 1.0, v73
	v_rcp_f32_e32 v98, v73
	v_add_f32_e32 v73, 1.0, v75
	v_mul_f32_e32 v75, 0xbfb8aa3b, v62
	v_exp_f32_e32 v75, v75
	v_mul_f32_e32 v77, 0xbfb8aa3b, v63
	v_exp_f32_e32 v77, v77
	v_rcp_f32_e32 v99, v73
	v_add_f32_e32 v73, 1.0, v75
	v_rcp_f32_e32 v100, v73
	v_add_f32_e32 v73, 1.0, v77
	v_rcp_f32_e32 v101, v73
	v_pk_mul_f32 v[52:53], v[52:53], v[96:97] op_sel_hi:[1,0]
	v_pk_mul_f32 v[60:61], v[60:61], v[98:99]
	v_pk_mul_f32 v[54:55], v[54:55], v[96:97] op_sel_hi:[1,0]
	v_pk_mul_f32 v[52:53], v[52:53], v[60:61]
	v_pk_mul_f32 v[60:61], v[62:63], v[100:101]
	v_pk_mul_f32 v[56:57], v[56:57], v[96:97] op_sel_hi:[1,0]
	v_pk_mul_f32 v[54:55], v[54:55], v[60:61]
	v_mul_f32_e32 v62, 0xbfb8aa3b, v56
	v_mul_f32_e32 v60, 0xbfb8aa3b, v57
	v_exp_f32_e32 v62, v62
	v_exp_f32_e32 v61, v60
	v_pk_mul_f32 v[58:59], v[58:59], v[96:97] op_sel_hi:[1,0]
	v_pk_mul_f32 v[48:49], v[48:49], v[96:97] op_sel_hi:[1,0]
	v_add_f32_e32 v60, 1.0, v62
	v_add_f32_e32 v61, 1.0, v61
	v_mul_f32_e32 v62, 0xbfb8aa3b, v58
	v_mul_f32_e32 v63, 0xbfb8aa3b, v59
	v_rcp_f32_e32 v60, v60
	v_rcp_f32_e32 v61, v61
	v_exp_f32_e32 v62, v62
	v_exp_f32_e32 v63, v63
	v_mov_b64_e32 v[64:65], v[220:221]
	v_mov_b64_e32 v[66:67], v[222:223]
	s_nop 0
	v_mov_b64_e32 v[68:69], v[224:225]
	v_mov_b64_e32 v[70:71], v[226:227]
	v_pk_mul_f32 v[56:57], v[56:57], v[60:61]
	v_add_f32_e32 v60, 1.0, v62
	v_add_f32_e32 v61, 1.0, v63
	v_pk_add_f32 v[62:63], v[80:81], v[84:85]
	v_rcp_f32_e32 v60, v60
	v_pk_mov_b32 v[80:81], v[78:79], v[62:63] op_sel:[1,0]
	v_mov_b32_e32 v79, v63
	v_pk_add_f32 v[62:63], v[80:81], v[78:79]
	v_rcp_f32_e32 v61, v61
	v_add_f32_e32 v62, v62, v63
	ds_bpermute_b32 v63, v161, v62
	v_pk_mul_f32 v[56:57], v[48:49], v[56:57]
	v_pk_mul_f32 v[48:49], v[50:51], v[96:97] op_sel_hi:[1,0]
	v_pk_mul_f32 v[50:51], v[58:59], v[60:61]
	s_waitcnt lgkmcnt(0)
; __device__ __forceinline__ float fast_sigmoid(float v) { return __builtin_amdgcn_rcpf(1.0f + __builtin_amdgcn_exp2f(-1.4426950408889634f * v)); }
; __device__ __forceinline__ u32x4 pack8(const float* v) { u32x4 w; w.x = cvt_pk_bf16(v[0], v[1]); w.y = cvt_pk_bf16(v[2], v[3]); w.z = cvt_pk_bf16(v[4], v[5]); w.w = cvt_pk_bf16(v[6], v[7]); return w; }
;     __device__ __forceinline__ void operator()(int row, int pn, int within, const float* a, const float* b, float) const { (void)apply(row, pn, within, a, b); }
;     __device__ __forceinline__ void operator()(int row, int pn, int within, const float* a, const float* b, float) const { Pre p = preload(row, pn, within, 0); finish(row, pn, within, a, b, p); }
;     __device__ __forceinline__ void finish(int row, int pn, int within, const float* a, const float* b, const Pre& p) const {
;         const f32x4 s4 = p.s0 + p.s1; float sm = (s4[0] + s4[1]) + (s4[2] + s4[3]); sm += __shfl_xor(sm, 16); sm += __shfl_xor(sm, 32);
;         (*this)(row, pn, within, a, b, __builtin_amdgcn_rsqf(sm * (1.0f / DM) + EPS)); }
;     __device__ __forceinline__ void operator()(int row, int pn, int within, const float* a, const float* b, float rc) const {
;         float o[8];
; #pragma unroll
;         for (int j = 0; j < 8; ++j) { const float g = a[j] * rc, u = b[j] * rc; o[j] = g * fast_sigmoid(g) * u; }
;         *(u32x4*)(hidden + (size_t)row * DFF + pn * 128 + within) = pack8(o);
	v_add_f32_e32 v60, v62, v63
	ds_bpermute_b32 v61, v155, v60
	v_pk_mul_f32 v[58:59], v[48:49], v[50:51]
	v_cvt_pk_bf16_f32 v48, v52, v53
	v_cvt_pk_bf16_f32 v49, v54, v55
	v_mad_i64_i32 v[54:55], s[26:27], v94, s52, v[152:153]
	s_waitcnt lgkmcnt(0)
	v_add_f32_e32 v52, v60, v61
	v_fmamk_f32 v52, v52, 0x3a000000, v171
	v_rsq_f32_e32 v52, v52
	v_lshl_add_u64 v[54:55], v[54:55], 0, s[24:25]
	v_cvt_pk_bf16_f32 v50, v56, v57
	v_cvt_pk_bf16_f32 v51, v58, v59
	v_pk_mul_f32 v[44:45], v[44:45], v[52:53] op_sel_hi:[1,0]
	v_lshl_add_u64 v[54:55], v[54:55], 0, v[112:113]
	v_mul_f32_e32 v53, 0xbfb8aa3b, v44
	v_exp_f32_e32 v53, v53
	global_store_dwordx4 v[54:55], v[48:51], off
	v_pk_mul_f32 v[46:47], v[46:47], v[52:53] op_sel_hi:[1,0]
	s_nop 0
	v_mul_f32_e32 v48, 0xbfb8aa3b, v45
	v_exp_f32_e32 v49, v48
	v_mul_f32_e32 v50, 0xbfb8aa3b, v46
	v_mul_f32_e32 v51, 0xbfb8aa3b, v47
	v_exp_f32_e32 v50, v50
	v_exp_f32_e32 v51, v51
	v_add_f32_e32 v48, 1.0, v53
	v_add_f32_e32 v49, 1.0, v49
	v_rcp_f32_e32 v48, v48
	v_rcp_f32_e32 v49, v49
	v_add_f32_e32 v50, 1.0, v50
	v_add_f32_e32 v51, 1.0, v51
	v_rcp_f32_e32 v50, v50
	v_rcp_f32_e32 v51, v51
	v_pk_mul_f32 v[36:37], v[36:37], v[52:53] op_sel_hi:[1,0]
	v_pk_mul_f32 v[44:45], v[44:45], v[48:49]
	v_pk_mul_f32 v[38:39], v[38:39], v[52:53] op_sel_hi:[1,0]
	v_pk_mul_f32 v[36:37], v[36:37], v[44:45]
	v_pk_mul_f32 v[44:45], v[46:47], v[50:51]
	v_pk_mul_f32 v[40:41], v[40:41], v[52:53] op_sel_hi:[1,0]
	v_pk_mul_f32 v[38:39], v[38:39], v[44:45]
	v_mul_f32_e32 v46, 0xbfb8aa3b, v40
	v_mul_f32_e32 v44, 0xbfb8aa3b, v41
	v_exp_f32_e32 v46, v46
	v_exp_f32_e32 v45, v44
	v_pk_mul_f32 v[42:43], v[42:43], v[52:53] op_sel_hi:[1,0]
	v_pk_add_f32 v[48:49], v[86:87], v[90:91]
	v_add_f32_e32 v44, 1.0, v46
	v_add_f32_e32 v45, 1.0, v45
	v_mul_f32_e32 v46, 0xbfb8aa3b, v42
	v_mul_f32_e32 v47, 0xbfb8aa3b, v43
	v_rcp_f32_e32 v44, v44
	v_rcp_f32_e32 v45, v45
	v_exp_f32_e32 v46, v46
	v_exp_f32_e32 v47, v47
	v_pk_mul_f32 v[32:33], v[32:33], v[52:53] op_sel_hi:[1,0]
	v_pk_mul_f32 v[40:41], v[40:41], v[44:45]
	v_add_f32_e32 v44, 1.0, v46
	v_add_f32_e32 v45, 1.0, v47
	v_pk_add_f32 v[46:47], v[88:89], v[92:93]
	v_rcp_f32_e32 v44, v44
	v_pk_mov_b32 v[50:51], v[48:49], v[46:47] op_sel:[1,0]
	v_mov_b32_e32 v49, v47
	v_pk_add_f32 v[46:47], v[50:51], v[48:49]
	v_rcp_f32_e32 v45, v45
	v_add_f32_e32 v46, v46, v47
	ds_bpermute_b32 v47, v161, v46
	v_pk_mul_f32 v[40:41], v[32:33], v[40:41]
	v_pk_mul_f32 v[32:33], v[34:35], v[52:53] op_sel_hi:[1,0]
	v_pk_mul_f32 v[34:35], v[42:43], v[44:45]
	s_waitcnt lgkmcnt(0)
	v_add_f32_e32 v44, v46, v47
	ds_bpermute_b32 v45, v155, v44
	v_pk_mul_f32 v[42:43], v[32:33], v[34:35]
	v_cvt_pk_bf16_f32 v32, v36, v37
	v_cvt_pk_bf16_f32 v33, v38, v39
	v_mad_i64_i32 v[38:39], s[26:27], v76, s52, v[152:153]
	s_waitcnt lgkmcnt(0)
; __device__ __forceinline__ float fast_sigmoid(float v) { return __builtin_amdgcn_rcpf(1.0f + __builtin_amdgcn_exp2f(-1.4426950408889634f * v)); }
; __device__ __forceinline__ u32x4 pack8(const float* v) { u32x4 w; w.x = cvt_pk_bf16(v[0], v[1]); w.y = cvt_pk_bf16(v[2], v[3]); w.z = cvt_pk_bf16(v[4], v[5]); w.w = cvt_pk_bf16(v[6], v[7]); return w; }
;     __device__ __forceinline__ void operator()(int row, int pn, int within, const float* a, const float* b, float) const { (void)apply(row, pn, within, a, b); }
;     __device__ __forceinline__ void operator()(int row, int pn, int within, const float* a, const float* b, float) const { Pre p = preload(row, pn, within, 0); finish(row, pn, within, a, b, p); }
; #define PG8_GATHER(ai, m) float a[8], b[8]; _Pragma("unroll") for (int j = 0; j < 4; ++j) { a[j] = acc[ai][0][m][0][j]; a[4 + j] = acc[ai][0][m][1][j]; b[j] = acc[ai][1][m][0][j]; b[4 + j] = acc[ai][1][m][1][j]; }
;     __device__ __forceinline__ void finish(int row, int pn, int within, const float* a, const float* b, const Pre& p) const {
;         const f32x4 s4 = p.s0 + p.s1; float sm = (s4[0] + s4[1]) + (s4[2] + s4[3]); sm += __shfl_xor(sm, 16); sm += __shfl_xor(sm, 32);
;         (*this)(row, pn, within, a, b, __builtin_amdgcn_rsqf(sm * (1.0f / DM) + EPS)); }
;     __device__ __forceinline__ void operator()(int row, int pn, int within, const float* a, const float* b, float rc) const {
;         float o[8];
; #pragma unroll
;         for (int j = 0; j < 8; ++j) { const float g = a[j] * rc, u = b[j] * rc; o[j] = g * fast_sigmoid(g) * u; }
;         *(u32x4*)(hidden + (size_t)row * DFF + pn * 128 + within) = pack8(o);
; template <class Epi> __device__ __forceinline__ void run_epi(const Epi& E, const f32x4 (&acc)[2][2][4][2], const Unit& u, int wr, int wc, int fr, int fq) {
;     ...
;     for (int ai = 0; ai < 2; ++ai) { const int row0 = u.pm * BM + ai * HALF + wr * 64 + fr; typename Epi::Pre pre[4];
; #pragma unroll
;         for (int m = 0; m < 4; ++m) pre[m] = E.preload(row0 + m * 16, u.pn, within, fq);
; #pragma unroll
;         for (int m = 0; m < 4; ++m) { PG8_GATHER(ai, m); E.finish(row0 + m * 16, u.pn, within, a, b, pre[m]); } }
	v_add_f32_e32 v36, v44, v45
	v_fmamk_f32 v36, v36, 0x3a000000, v171
	v_rsq_f32_e32 v36, v36
	v_lshl_add_u64 v[38:39], v[38:39], 0, s[24:25]
	v_cvt_pk_bf16_f32 v34, v40, v41
	v_cvt_pk_bf16_f32 v35, v42, v43
	v_pk_mul_f32 v[28:29], v[28:29], v[36:37] op_sel_hi:[1,0]
	v_lshl_add_u64 v[38:39], v[38:39], 0, v[112:113]
	v_mul_f32_e32 v37, 0xbfb8aa3b, v28
	v_exp_f32_e32 v37, v37
	global_store_dwordx4 v[38:39], v[32:35], off
	v_pk_mul_f32 v[30:31], v[30:31], v[36:37] op_sel_hi:[1,0]
	s_nop 0
	v_mul_f32_e32 v32, 0xbfb8aa3b, v29
	v_exp_f32_e32 v33, v32
	v_mul_f32_e32 v34, 0xbfb8aa3b, v30
	v_mul_f32_e32 v35, 0xbfb8aa3b, v31
	v_exp_f32_e32 v34, v34
	v_exp_f32_e32 v35, v35
	v_add_f32_e32 v32, 1.0, v37
	v_add_f32_e32 v33, 1.0, v33
	v_rcp_f32_e32 v32, v32
	v_rcp_f32_e32 v33, v33
	v_add_f32_e32 v34, 1.0, v34
	v_add_f32_e32 v35, 1.0, v35
	v_rcp_f32_e32 v34, v34
	v_rcp_f32_e32 v35, v35
	v_pk_mul_f32 v[20:21], v[20:21], v[36:37] op_sel_hi:[1,0]
	v_pk_mul_f32 v[28:29], v[28:29], v[32:33]
	v_pk_mul_f32 v[22:23], v[22:23], v[36:37] op_sel_hi:[1,0]
	v_pk_mul_f32 v[20:21], v[20:21], v[28:29]
	v_pk_mul_f32 v[28:29], v[30:31], v[34:35]
	v_pk_mul_f32 v[24:25], v[24:25], v[36:37] op_sel_hi:[1,0]
	v_pk_mul_f32 v[22:23], v[22:23], v[28:29]
	v_mul_f32_e32 v30, 0xbfb8aa3b, v24
	v_mul_f32_e32 v28, 0xbfb8aa3b, v25
	v_exp_f32_e32 v30, v30
	v_exp_f32_e32 v29, v28
	v_pk_mul_f32 v[26:27], v[26:27], v[36:37] op_sel_hi:[1,0]
	v_pk_add_f32 v[32:33], v[64:65], v[68:69]
	v_add_f32_e32 v28, 1.0, v30
	v_add_f32_e32 v29, 1.0, v29
	v_mul_f32_e32 v30, 0xbfb8aa3b, v26
	v_mul_f32_e32 v31, 0xbfb8aa3b, v27
	v_rcp_f32_e32 v28, v28
	v_rcp_f32_e32 v29, v29
	v_exp_f32_e32 v30, v30
	v_exp_f32_e32 v31, v31
	v_pk_mul_f32 v[16:17], v[16:17], v[36:37] op_sel_hi:[1,0]
	v_pk_mul_f32 v[24:25], v[24:25], v[28:29]
	v_add_f32_e32 v28, 1.0, v30
	v_add_f32_e32 v29, 1.0, v31
	v_pk_add_f32 v[30:31], v[66:67], v[70:71]
	v_rcp_f32_e32 v28, v28
	v_pk_mov_b32 v[34:35], v[32:33], v[30:31] op_sel:[1,0]
	v_mov_b32_e32 v33, v31
	v_pk_add_f32 v[30:31], v[34:35], v[32:33]
	v_rcp_f32_e32 v29, v29
	v_add_f32_e32 v30, v30, v31
	ds_bpermute_b32 v31, v161, v30
	v_pk_mul_f32 v[24:25], v[16:17], v[24:25]
	v_pk_mul_f32 v[16:17], v[18:19], v[36:37] op_sel_hi:[1,0]
	v_pk_mul_f32 v[18:19], v[26:27], v[28:29]
	s_waitcnt lgkmcnt(0)
	v_add_f32_e32 v28, v30, v31
	ds_bpermute_b32 v29, v155, v28
	v_pk_mul_f32 v[26:27], v[16:17], v[18:19]
	v_cvt_pk_bf16_f32 v16, v20, v21
	v_cvt_pk_bf16_f32 v17, v22, v23
	v_mad_i64_i32 v[22:23], s[26:27], v74, s52, v[152:153]
	s_waitcnt lgkmcnt(0)
	v_add_f32_e32 v20, v28, v29
	v_fmamk_f32 v20, v20, 0x3a000000, v171
	v_rsq_f32_e32 v20, v20
	v_lshl_add_u64 v[22:23], v[22:23], 0, s[24:25]
	v_cvt_pk_bf16_f32 v18, v24, v25
	v_cvt_pk_bf16_f32 v19, v26, v27
	v_pk_mul_f32 v[12:13], v[12:13], v[20:21] op_sel_hi:[1,0]
	v_lshl_add_u64 v[22:23], v[22:23], 0, v[112:113]
	v_mul_f32_e32 v21, 0xbfb8aa3b, v12
	v_exp_f32_e32 v21, v21
	global_store_dwordx4 v[22:23], v[16:19], off
	v_pk_mul_f32 v[14:15], v[14:15], v[20:21] op_sel_hi:[1,0]
	s_nop 0
	v_mul_f32_e32 v16, 0xbfb8aa3b, v13
	v_exp_f32_e32 v17, v16
	v_mul_f32_e32 v18, 0xbfb8aa3b, v14
	v_mul_f32_e32 v19, 0xbfb8aa3b, v15
	v_exp_f32_e32 v18, v18
	v_exp_f32_e32 v19, v19
	v_add_f32_e32 v16, 1.0, v21
	v_add_f32_e32 v17, 1.0, v17
	v_rcp_f32_e32 v16, v16
	v_rcp_f32_e32 v17, v17
	v_add_f32_e32 v18, 1.0, v18
	v_add_f32_e32 v19, 1.0, v19
	v_rcp_f32_e32 v18, v18
	v_rcp_f32_e32 v19, v19
	v_pk_mul_f32 v[4:5], v[4:5], v[20:21] op_sel_hi:[1,0]
	v_pk_mul_f32 v[12:13], v[12:13], v[16:17]
	v_pk_mul_f32 v[8:9], v[8:9], v[20:21] op_sel_hi:[1,0]
	v_pk_mul_f32 v[4:5], v[4:5], v[12:13]
	v_pk_mul_f32 v[12:13], v[14:15], v[18:19]
	v_mul_f32_e32 v14, 0xbfb8aa3b, v8
	v_exp_f32_e32 v14, v14
	v_pk_mul_f32 v[6:7], v[6:7], v[20:21] op_sel_hi:[1,0]
	v_pk_mul_f32 v[10:11], v[10:11], v[20:21] op_sel_hi:[1,0]
	v_pk_mul_f32 v[6:7], v[6:7], v[12:13]
	v_mul_f32_e32 v12, 0xbfb8aa3b, v9
	v_exp_f32_e32 v13, v12
	v_add_f32_e32 v12, 1.0, v14
	v_mul_f32_e32 v14, 0xbfb8aa3b, v10
	v_mul_f32_e32 v15, 0xbfb8aa3b, v11
	v_exp_f32_e32 v14, v14
	v_exp_f32_e32 v15, v15
	v_add_f32_e32 v13, 1.0, v13
	v_rcp_f32_e32 v12, v12
	v_rcp_f32_e32 v13, v13
	v_add_f32_e32 v14, 1.0, v14
	v_add_f32_e32 v15, 1.0, v15
	v_rcp_f32_e32 v14, v14
	v_rcp_f32_e32 v15, v15
	v_pk_mul_f32 v[0:1], v[0:1], v[20:21] op_sel_hi:[1,0]
	v_pk_mul_f32 v[8:9], v[8:9], v[12:13]
	s_nop 0
	v_pk_mul_f32 v[8:9], v[0:1], v[8:9]
	v_pk_mul_f32 v[0:1], v[2:3], v[20:21] op_sel_hi:[1,0]
	v_pk_mul_f32 v[2:3], v[10:11], v[14:15]
	s_nop 0
	v_pk_mul_f32 v[10:11], v[0:1], v[2:3]
	v_cvt_pk_bf16_f32 v0, v4, v5
	v_mad_i64_i32 v[4:5], s[26:27], v72, s52, v[152:153]
	v_lshl_add_u64 v[4:5], v[4:5], 0, s[24:25]
	v_cvt_pk_bf16_f32 v1, v6, v7
	v_cvt_pk_bf16_f32 v2, v8, v9
	v_cvt_pk_bf16_f32 v3, v10, v11
	v_lshl_add_u64 v[4:5], v[4:5], 0, v[112:113]
	global_store_dwordx4 v[4:5], v[0:3], off
	s_cbranch_vccnz .LBB0_592
	s_andn2_b64 vcc, exec, s[6:7]
	s_cbranch_vccnz .LBB0_591
	s_barrier
	s_branch .LBB0_591
